# mlp_out: row panels dealt in reverse order (most recently written H rows are read first) for memory-side cache reuse
# speedup vs baseline: 1.0101x; 1.0043x over previous
; template <class EpiT, bool ALIGN_EPI>
; __device__ __forceinline__ void gemm_phase(LAS unsigned char* lds, const Gemm g, const StaticOrder& S, const EpiT& E, const int tid) {
;     const int wid = __builtin_amdgcn_readfirstlane(tid >> 6), lane = tid & 63, wr = wid >> 2, wc = wid & 3, fr = lane & 15, fq = lane >> 4;
;     const int K = g.K;
;     unsigned voffA[2], voffB[2];
; #pragma unroll
;     for (int i = 0; i < 2; ++i) { int R, C; stage_rc(tid * 16 + i * 8192, R, C); const int Rb = (R & ~31) + perm32(R & 31);
;         voffA[i] = (unsigned)(R * K + C) * 2u; voffB[i] = (unsigned)(Rb * K + C) * 2u; }
;     const size_t kstep = (size_t)(BK * 2);
;     const size_t hstep = (size_t)HALF * K * 2;
;     const size_t tstep = 2 * hstep;
;     const unsigned ldsw = (unsigned)wid * 1024u;
;     const int aoff = lds_byte(wr * 64 + fr, fq * 8), boff = lds_byte(wc * 32 + fr, fq * 8);
;     ...
;     Unit cur, nxt; int ui = 0;
;     if (!S.next(0, cur)) return;
;     f32x4 acc[2][2][4][2];
; #pragma unroll
;     for (int a = 0; a < 2; ++a)
; #pragma unroll
;         for (int b = 0; b < 2; ++b)
; #pragma unroll
;             for (int m = 0; m < 4; ++m)
; #pragma unroll
;                 for (int n = 0; n < 2; ++n) acc[a][b][m][n] = (f32x4){0.f, 0.f, 0.f, 0.f};
;     bf16x8 At[4][2], B0[2][2], B1[2][2];
;     const char* cA; const char* cB; PG8_PTRS(cur, cA, cB);
;     PG8_STAGE(PG8_SB(0, 0), cB, voffB); PG8_STAGE(PG8_SB(0, 1), cB + hstep, voffB); PG8_STAGE(PG8_SA(0, 0), cA, voffA); PG8_STAGE(PG8_SA(0, 1), cA + hstep, voffA);
; __global__ void __launch_bounds__(NTHR) fwd_kernel(Params p) {
;     ...
;             } else if (s == 5) {
;                 pg8::Gemm g{(const bf16_t*)(q.ws + WS_H), (const bf16_t*)(q.ws + WS_W2) + (size_t)l * DM * FF, FF, 1 << 30};
;                 pg8::StaticOrder S; S.init(ML / 256, 4, G, (int)blockIdx.x, last ? 0 : MC / 256);
;                 pg8::FuseArgs fa{}; fa.ws = q.ws; fa.xoutf = q.out; fa.modl = mod + (size_t)l * 9 * NMOD; fa.modn = mod + (size_t)(last ? l : l + 1) * 9 * NMOD; fa.gpost = q.in[I_GPOSTMLP] + l * DM; fa.gpre = q.in[I_GPREMIX] + (last ? l : l + 1) * DM;
;                 fa.gate_off = 5 * DM; fa.sh_off = 0; fa.sc_off = DM; fa.cbank = l * 4 + 2; fa.write_xn = last ? 0 : 1; fa.out_f32 = last ? 1 : 0;
;                 pg8::Epi<1> E{XN, nullptr, q.out, fa};
;                 pg8::gemm_phase<pg8::Epi<1>, true>(lds, g, S, E, tid);
.LBB0_35:
	s_add_i32 s0, s56, -2
	s_mul_hi_i32 s1, s0, 0x92492493
	s_add_i32 s1, s1, s0
	s_lshr_b32 s4, s1, 31
	s_ashr_i32 s1, s1, 2
	s_add_i32 s6, s1, s4
	s_mov_b32 s4, s6
	v_writelane_b32 v255, s4, 17
	s_mul_i32 s1, s6, 7
	v_readlane_b32 s36, v254, 42
	v_writelane_b32 v255, s5, 18
	s_sub_i32 s4, s0, s1
	s_sub_i32 s0, s56, 30
	s_cmp_gt_u32 s0, -8
	s_cselect_b64 s[16:17], -1, 0
	s_cmp_lt_u32 s0, -7
	s_cselect_b64 s[0:1], -1, 0
	v_writelane_b32 v255, s0, 19
	v_readlane_b32 s50, v254, 56
	v_readlane_b32 s37, v254, 43
	v_writelane_b32 v255, s1, 20
	s_and_b64 s[0:1], s[0:1], exec
	s_movk_i32 s0, 0x88
	s_cselect_b32 s97, s0, 0x80
	v_readlane_b32 s38, v254, 44
	v_readlane_b32 s39, v254, 45
	v_readlane_b32 s40, v254, 46
	v_readlane_b32 s41, v254, 47
	v_readlane_b32 s42, v254, 48
	v_readlane_b32 s43, v254, 49
	v_readlane_b32 s44, v254, 50
	v_readlane_b32 s45, v254, 51
	v_readlane_b32 s46, v254, 52
	v_readlane_b32 s47, v254, 53
	v_readlane_b32 s48, v254, 54
	v_readlane_b32 s49, v254, 55
	v_readlane_b32 s51, v254, 57
	s_add_u32 s0, s50, s92
	v_writelane_b32 v255, s0, 21
	s_addc_u32 s0, s51, s93
	v_readlane_b32 s36, v254, 58
	v_writelane_b32 v255, s0, 23
	v_readlane_b32 s38, v254, 60
	v_readlane_b32 s39, v254, 61
	v_readlane_b32 s46, v255, 4
	s_add_u32 s0, s38, s92
	v_readlane_b32 s42, v255, 0
	v_readlane_b32 s43, v255, 1
	v_readlane_b32 s44, v255, 2
	v_readlane_b32 s45, v255, 3
	v_readlane_b32 s47, v255, 5
	v_readlane_b32 s48, v255, 6
	v_readlane_b32 s49, v255, 7
	v_readlane_b32 s50, v255, 8
	v_readlane_b32 s51, v255, 9
	s_mov_b32 s46, s4
	v_writelane_b32 v255, s0, 24
	s_addc_u32 s0, s39, s93
	v_readlane_b32 s4, v254, 38
	v_writelane_b32 v255, s0, 25
	v_readlane_b32 s6, v254, 40
	v_readlane_b32 s7, v254, 41
	s_add_u32 s42, s6, s92
	v_writelane_b32 v255, s56, 26
	s_addc_u32 s43, s7, s93
	v_writelane_b32 v255, s94, 27
	s_mov_b64 s[0:1], -1
	s_mov_b64 s[50:51], 0
	s_cmp_lt_i32 s46, 3
	s_mov_b64 s[48:49], 0
	s_mov_b32 s38, s87
	v_writelane_b32 v255, s95, 28
	v_readlane_b32 s37, v254, 59
	v_readlane_b32 s40, v254, 62
	v_readlane_b32 s41, v254, 63
	v_readlane_b32 s5, v254, 39
	s_cbranch_scc1 .LBB0_223
	s_cmp_gt_i32 s46, 3
	s_cbranch_scc0 .LBB0_191
	s_cmp_gt_i32 s46, 4
	s_cbranch_scc0 .LBB0_171
	s_cmp_eq_u32 s46, 5
	s_mov_b64 s[48:49], -1
	s_cbranch_scc0 .LBB0_170
	v_readlane_b32 s0, v255, 19
	v_readlane_b32 s1, v255, 20
	s_and_b64 s[0:1], s[0:1], exec
	s_movk_i32 s0, 0x300
	s_cselect_b32 s18, s0, 0x200
	s_cmp_ge_i32 s2, s18
	s_cselect_b64 s[0:1], -1, 0
	v_readfirstlane_b32 s8, v166
	s_and_b64 vcc, exec, s[0:1]
	s_cbranch_vccnz .LBB0_169
	s_waitcnt vmcnt(0)
	v_lshlrev_b32_e32 v0, 4, v166
	v_add_u32_e32 v1, 0x2000, v0
	v_readlane_b32 s4, v255, 17
	v_ashrrev_i32_e32 v2, 31, v1
	s_add_u32 s14, s73, 0xa800000
	v_readlane_b32 s5, v255, 18
	v_lshrrev_b32_e32 v2, 22, v2
	s_addc_u32 s15, s57, 0
	s_mov_b32 s6, s4
	s_ashr_i32 s7, s4, 31
	v_writelane_b32 v255, s4, 17
	v_add_u32_e32 v2, v1, v2
	s_waitcnt vmcnt(1)
	v_ashrrev_i32_e32 v8, 10, v2
	v_writelane_b32 v255, s5, 18
	s_lshl_b64 s[4:5], s[6:7], 23
	s_add_u32 s4, s73, s4
	v_mul_i32_i24_e32 v2, 0x400, v8
	s_addc_u32 s5, s57, s5
	v_sub_u32_e32 v1, v1, v2
	s_add_u32 s36, s4, 0x4400000
	v_lshrrev_b32_e32 v2, 4, v1
	s_addc_u32 s37, s5, 0
	v_readlane_b32 s4, v254, 4
	v_bitop3_b32 v1, v2, v1, 32 bitop3:0x6c
	s_ashr_i32 s6, s8, 6
	v_readlane_b32 s5, v254, 5
	v_ashrrev_i32_e32 v2, 31, v1
	s_ashr_i32 s7, s8, 8
	s_lshl_b32 s64, s6, 10
	s_or_b64 s[0:1], s[0:1], s[4:5]
	v_lshrrev_b32_e32 v2, 26, v2
	s_and_b64 s[0:1], s[0:1], exec
	v_add_u32_e32 v2, v1, v2
	v_lshlrev_b32_e32 v3, 3, v8
	v_readlane_b32 s0, v253, 11
	v_ashrrev_i32_e32 v9, 6, v2
	v_and_b32_e32 v3, -16, v3
	s_cselect_b32 s20, s0, -1
	v_readlane_b32 s0, v253, 12
	v_readlane_b32 s1, v253, 56
	v_add_u32_e32 v3, v9, v3
	s_cselect_b32 s22, s0, s1
	v_and_b32_e32 v4, 3, v9
	s_mov_b32 s0, 0x7ffe0
	v_lshrrev_b32_e32 v5, 2, v3
	v_lshlrev_b32_e32 v6, 1, v3
	v_and_b32_e32 v2, 0xc0, v2
	v_and_or_b32 v4, v3, s0, v4
	v_and_b32_e32 v5, 4, v5
	v_and_b32_e32 v6, 24, v6
	v_sub_u32_e32 v1, v1, v2
	v_or3_b32 v4, v4, v5, v6
	v_lshlrev_b32_e32 v5, 5, v8
	v_ashrrev_i16_sdwa v1, v252, sext(v1) dst_sel:DWORD dst_unused:UNUSED_PAD src0_sel:DWORD src1_sel:BYTE_0
	v_and_b32_e32 v5, 32, v5
	v_bfe_i32 v10, v1, 0, 16
	v_add_lshl_u32 v1, v5, v10, 1
	v_lshl_add_u32 v152, v4, 13, v1
	v_lshl_add_u32 v154, v3, 13, v1
	v_bfe_i32 v1, v166, 27, 1
	v_lshrrev_b32_e32 v1, 22, v1
	v_add_u32_e32 v1, v0, v1
	v_and_b32_e32 v1, 0xfffffc00, v1
	v_sub_u32_e32 v0, v0, v1
	v_lshrrev_b32_e32 v1, 4, v0
	v_ashrrev_i32_e32 v2, 31, v166
	v_bitop3_b32 v0, v1, v0, 32 bitop3:0x6c
	v_lshrrev_b32_e32 v2, 26, v2
	v_ashrrev_i32_e32 v1, 31, v0
	v_add_u32_e32 v2, v166, v2
	v_lshrrev_b32_e32 v1, 26, v1
	s_waitcnt vmcnt(0)
	v_ashrrev_i32_e32 v12, 6, v2
	v_add_u32_e32 v1, v0, v1
	v_lshlrev_b32_e32 v2, 3, v12
	v_ashrrev_i32_e32 v11, 6, v1
	v_and_b32_e32 v2, -16, v2
	v_add_u32_e32 v2, v11, v2
	v_and_b32_e32 v3, 3, v11
	s_mov_b32 s21, s31
	v_and_or_b32 v3, v2, s0, v3
	s_lshl_b64 s[0:1], s[20:21], 10
	v_readlane_b32 s24, v254, 6
	s_and_b64 s[4:5], s[4:5], exec
	v_readlane_b32 s25, v254, 7
	s_cselect_b32 s4, s1, 0
	s_cselect_b32 s5, s0, 0
	s_ashr_i32 s25, s24, 31
	s_sub_i32 s0, 0x7f, s24
	s_mov_b32 s1, 0
	s_lshl_b64 s[0:1], s[0:1], 21
	s_add_u32 s0, s14, s0
	s_addc_u32 s1, s15, s1
	s_add_u32 s70, s0, s5
	s_addc_u32 s71, s1, s4
	s_ashr_i32 s23, s22, 31
	v_lshrrev_b32_e32 v4, 2, v2
	v_lshlrev_b32_e32 v5, 1, v2
	v_and_b32_e32 v1, 0xc0, v1
	s_lshl_b64 s[0:1], s[22:23], 21
	v_and_b32_e32 v4, 4, v4
	v_and_b32_e32 v5, 24, v5
	v_sub_u32_e32 v0, v0, v1
	s_add_u32 s0, s36, s0
	v_or3_b32 v3, v3, v4, v5
	v_lshlrev_b32_e32 v4, 5, v12
	v_ashrrev_i16_sdwa v0, v252, sext(v0) dst_sel:DWORD dst_unused:UNUSED_PAD src0_sel:DWORD src1_sel:BYTE_0
	s_addc_u32 s1, s37, s1
	v_and_b32_e32 v4, 32, v4
	v_bfe_i32 v13, v0, 0, 16
	s_add_u32 s68, s0, s5
	v_add_lshl_u32 v0, v4, v13, 1
	s_addc_u32 s69, s1, s4
	s_add_i32 s76, s64, 0
	v_lshl_add_u32 v156, v3, 13, v0
	s_add_i32 m0, s76, 0x10000
	v_lshl_add_u32 v170, v2, 13, v0
	global_load_lds_dwordx4 v156, s[68:69]
	s_add_i32 m0, s76, 0x12000
	s_add_u32 s0, s68, 0x100000
	global_load_lds_dwordx4 v152, s[68:69]
	s_addc_u32 s1, s69, 0
	s_add_i32 m0, s76, 0x14000
	s_add_i32 s77, s76, 0x2000
	global_load_lds_dwordx4 v156, s[0:1]
	s_add_i32 m0, s76, 0x16000
	v_mov_b32_e32 v153, v157
	global_load_lds_dwordx4 v152, s[0:1]
	s_mov_b32 m0, s76
	s_add_u32 s0, s70, 0x100000
	global_load_lds_dwordx4 v170, s[70:71]
	s_mov_b32 m0, s77
	s_addc_u32 s1, s71, 0
	s_add_i32 s74, s76, 0x4000
	global_load_lds_dwordx4 v154, s[70:71]
	s_mov_b32 m0, s74
	s_add_i32 s75, s76, 0x6000
	global_load_lds_dwordx4 v170, s[0:1]
	s_mov_b32 m0, s75
	v_mov_b32_e32 v171, v157
	global_load_lds_dwordx4 v154, s[0:1]
	v_mov_b32_e32 v155, v157
	s_cmp_eq_u32 s7, 1
	v_lshl_add_u64 v[6:7], s[68:69], 0, v[156:157]
	v_lshl_add_u64 v[4:5], s[68:69], 0, v[152:153]
	v_lshl_add_u64 v[0:1], s[70:71], 0, v[170:171]
	s_cselect_b64 s[40:41], -1, 0
	s_cmp_lg_u32 s7, 1
	v_lshl_add_u64 v[2:3], s[70:71], 0, v[154:155]
	s_cbranch_scc1 .LBB0_42
	s_barrier
; #define LAS __attribute__((address_space(3)))
; #define PG8_STAGE(bufoff, gbase, voff) do { _Pragma("unroll") for (int _i = 0; _i < 2; ++_i) \
;         __builtin_amdgcn_global_load_lds((const unsigned*)((const char*)(gbase) + (voff)[_i]), (LAS unsigned*)(lds + (bufoff) + ldsw + _i * 8192), 16, 0, 0); } while (0)
; #define PG8_WAIT_V(n) asm volatile("s_waitcnt vmcnt(" #n ")" ::: "memory")
; #define PG8_BAR __builtin_amdgcn_s_barrier()
; __device__ __forceinline__ void fused_epi(f32x4 (&acc)[2][2][4][2], const Unit& u, int wr, int wc, int fr, int fq, LAS unsigned char* xl, int wid, int lane, const FuseArgs& f) {
;     const int pm = u.pm, pn = u.pn; const size_t mrow = (size_t)(pm >> 4) * NMOD;
;     const int colb = pn * BM + wc * 32 + 8 * fq;
;     const LAS float* S = (const LAS float*)(xl + 4096);
;     panel_rms(acc, pm, pn, wr, wc, fr, fq, xl, wid, lane, (float*)(f.ws + WS_SLOT1), (unsigned*)(f.ws + WS_CNT) + f.cbank * CNT_BANK);
;     {
;         f32x4 Gv[2][2];
; #pragma unroll
;         for (int bj = 0; bj < 2; ++bj)
; #pragma unroll
;             for (int n = 0; n < 2; ++n) { const int c = colb + bj * HALF + 4 * n; Gv[bj][n] = *(const f32x4*)(f.modl + f.gate_off + mrow + c) * *(const f32x4*)(f.gpost + c); }
; #pragma unroll
;         for (int ai = 0; ai < 2; ++ai)
; #pragma unroll
;             for (int m = 0; m < 4; ++m) { const int r = ai * HALF + wr * 64 + m * 16 + fr; const float rstd = S[r];
; template <class EpiT, bool ALIGN_EPI>
; __device__ __forceinline__ void gemm_phase(LAS unsigned char* lds, const Gemm g, const StaticOrder& S, const EpiT& E, const int tid) {
;     ...
;     PG8_STAGE(PG8_SB(0, 0), cB, voffB); PG8_STAGE(PG8_SB(0, 1), cB + hstep, voffB); PG8_STAGE(PG8_SA(0, 0), cA, voffA); PG8_STAGE(PG8_SA(0, 1), cA + hstep, voffA);
;     if (wr == 1) PG8_BAR;
;     PG8_WAIT_V(2); PG8_BAR;
;     PG8_STAGE(PG8_SB(1, 0), cB + kstep, voffB); PG8_STAGE(PG8_SA(1, 0), cA + kstep, voffA); PG8_STAGE(PG8_SB(1, 1), cB + hstep + kstep, voffB);
;     PG8_WAIT_V(6); PG8_BAR;
.LBB0_42:
	v_readlane_b32 s0, v255, 17
	v_readlane_b32 s1, v255, 18
	s_mov_b32 s4, s0
	s_mul_i32 s1, s4, 0x36000
	s_mul_hi_i32 s0, s0, 0x36000
	s_add_u32 s9, s73, s1
	s_addc_u32 s10, s57, s0
	s_lshl_b32 s0, s4, 10
	s_ashr_i32 s1, s0, 31
	s_lshl_b64 s[0:1], s[0:1], 2
	v_readlane_b32 s5, v255, 24
	s_add_u32 s48, s5, s0
	v_readlane_b32 s0, v255, 25
	s_addc_u32 s49, s0, s1
	s_and_b32 s11, s6, 3
	s_add_i32 m0, s76, 0x18000
	v_lshl_add_u64 v[6:7], v[6:7], 0, s[88:89]
	s_lshl_b32 s0, s4, 15
	s_lshl_b32 s1, s7, 13
	s_lshl_b32 s12, s11, 12
	s_waitcnt vmcnt(2)
	s_barrier
	global_load_lds_dwordx4 v[6:7], off
	v_lshl_add_u64 v[4:5], v[4:5], 0, s[88:89]
	s_add_i32 m0, s76, 0x1a000
	s_add_i32 s62, s76, 0x8000
	s_add_i32 s65, s76, 0xa000
	global_load_lds_dwordx4 v[4:5], off
	v_lshl_add_u64 v[0:1], v[0:1], 0, s[88:89]
	s_mov_b32 m0, s62
	s_add_u32 s4, s68, 0x100080
	global_load_lds_dwordx4 v[0:1], off
	v_lshl_add_u64 v[0:1], v[2:3], 0, s[88:89]
	s_mov_b32 m0, s65
	s_addc_u32 s5, s69, 0
	global_load_lds_dwordx4 v[0:1], off
	s_add_i32 m0, s76, 0x1c000
	v_lshl_add_u64 v[0:1], s[4:5], 0, v[156:157]
	global_load_lds_dwordx4 v[0:1], off
	v_lshl_add_u64 v[0:1], s[4:5], 0, v[152:153]
	s_add_i32 m0, s76, 0x1e000
	v_and_b32_e32 v2, 48, v166
	global_load_lds_dwordx4 v[0:1], off
	v_and_b32_e32 v0, 15, v166
	v_lshl_or_b32 v167, s7, 6, v0
	v_lshlrev_b32_e32 v3, 2, v167
	v_and_b32_e32 v4, 32, v3
	v_lshl_or_b32 v2, v0, 6, v2
	s_cmpk_lt_u32 s8, 0x100
	v_bitop3_b32 v4, v2, s1, v4 bitop3:0xde
	s_cselect_b64 s[26:27], -1, 0
	s_lshl_b32 s1, s11, 2
	v_lshlrev_b32_e32 v5, 2, v166
	s_add_i32 s1, s1, 0
	s_lshl_b32 s7, s7, 10
	v_and_b32_e32 v5, 32, v5
	s_add_i32 s1, s1, s7
	v_bitop3_b32 v194, s12, v2, v5 bitop3:0xf6
	s_add_i32 s12, s1, 0x20000
	v_cmp_eq_u32_e64 s[28:29], 0, v168
	v_and_b32_e32 v2, 31, v166
	s_cmp_lt_u32 s8, 64
	v_writelane_b32 v255, s28, 29
	v_lshrrev_b32_e32 v1, 1, v166
	v_lshl_or_b32 v195, s6, 5, v2
	v_writelane_b32 v255, s29, 30
	s_cselect_b64 s[28:29], -1, 0
	v_readlane_b32 s1, v254, 28
	v_or_b32_e32 v198, 16, v167
	v_or_b32_e32 v200, 32, v167
	v_or_b32_e32 v202, 48, v167
	v_add_u32_e32 v204, 0x80, v167
	v_add_u32_e32 v206, 0x90, v167
	v_add_u32_e32 v208, 0xa0, v167
	v_add_u32_e32 v210, 0xb0, v167
	s_add_u32 s44, s73, 0x180000
	v_and_b32_e32 v1, 24, v1
	v_lshl_add_u32 v196, v195, 2, s1
	v_add_u32_e32 v197, s1, v3
	v_lshl_add_u32 v199, v198, 2, s1
	v_lshl_add_u32 v201, v200, 2, s1
	v_lshl_add_u32 v203, v202, 2, s1
	v_lshl_add_u32 v205, v204, 2, s1
	v_lshl_add_u32 v207, v206, 2, s1
	v_lshl_add_u32 v209, v208, 2, s1
	v_lshl_add_u32 v211, v210, 2, s1
	s_addc_u32 s45, s57, 0
	s_ashr_i32 s1, s0, 31
	s_lshl_b64 s[0:1], s[0:1], 2
	v_lshl_or_b32 v213, s11, 5, v1
	v_lshlrev_b32_e32 v1, 16, v12
	s_add_u32 s0, s73, s0
	v_and_b32_e32 v1, 0xfffe0000, v1
	s_addc_u32 s1, s57, s1
	v_lshl_add_u32 v1, v11, 13, v1
	v_and_b32_e32 v3, 1, v12
	s_add_u32 s39, s0, 0x110000
	v_lshl_or_b32 v1, v3, 6, v1
	v_writelane_b32 v255, s28, 31
	s_addc_u32 s47, s1, 0
	v_lshl_add_u32 v172, v13, 1, v1
	v_lshlrev_b32_e32 v1, 16, v8
	v_writelane_b32 v255, s29, 32
	s_add_u32 s0, s9, 0x5000
	v_and_b32_e32 v1, 0xfffe0000, v1
	v_writelane_b32 v255, s0, 33
	s_addc_u32 s0, s10, 0
	v_lshl_add_u32 v1, v9, 13, v1
	v_and_b32_e32 v3, 1, v8
	s_waitcnt vmcnt(6)
	v_lshlrev_b32_e32 v2, 4, v195
	v_writelane_b32 v255, s0, 34
	v_lshl_or_b32 v1, v3, 6, v1
	s_mov_b32 s0, s24
	v_lshlrev_b32_e32 v0, 4, v0
	v_lshl_add_u32 v174, v10, 1, v1
	v_add_u32_e32 v1, 0, v2
	v_writelane_b32 v254, s0, 6
	v_cmp_gt_u32_e64 s[4:5], 16, v168
	v_cmp_gt_u32_e64 s[6:7], 32, v168
	s_mov_b32 s63, 0
	v_add_u32_e32 v212, 0xffff8000, v167
	s_mov_b32 s19, s31
	v_mov_b32_e32 v173, v157
	v_mov_b32_e32 v175, v157
	v_add_u32_e32 v214, 0, v4
	v_add_u32_e32 v215, 0x20000, v1
	v_add_u32_e32 v216, s12, v0
	v_writelane_b32 v254, s1, 7
	s_sub_i32 s53, 0x7f, s24
	s_barrier
	s_branch .LBB0_45

; #define PG8_PTRS(u, pa, pb) do { const size_t _ko = (u).ks >= 0 ? (size_t)(u).ks * (size_t)(K / KSPLIT) * 2 : 0; \
;         const char* _a = (const char*)g.A + (size_t)(u).pm * tstep + _ko; const char* _b = (const char*)g.Bt + (size_t)(u).pn * tstep + _ko; \
;         if ((u).pn >= g.nN_main) { pa = _b; pb = _a; } else { pa = _a; pb = _b; } } while (0)
;     __device__ __forceinline__ bool next(int i, Unit& u) const {
;         const long L = (long)i * G + c; if (L >= nwg + nsplit * nN * KSPLIT) return false;
;         int pm, pn, ks;
;         if (L >= nwg) { const int e = (int)L - nwg, cu = e / KSPLIT; ks = e % KSPLIT; pm = nM + cu / nN; pn = cu % nN; }
;         else {
;             int wgid = (int)L; { const int q = nwg / NXCD, r = nwg % NXCD, xcd = wgid % NXCD, off = wgid / NXCD; wgid = (xcd < r ? xcd * (q + 1) : r * (q + 1) + (xcd - r) * q) + off; }
;             const int nig = WGM * nN, gid = wgid / nig, fm = gid * WGM, gsz = (nM - fm) < WGM ? (nM - fm) : WGM;
;             pm = fm + ((wgid % nig) % gsz); pn = (wgid % nig) / gsz; ks = -1;
;         }
;         u.pm = pm; u.pn = pn; u.ks = ks; return true;
; template <class EpiT, bool ALIGN_EPI>
; __device__ __forceinline__ void gemm_phase(LAS unsigned char* lds, const Gemm g, const StaticOrder& S, const EpiT& E, const int tid) {
;     ...
;         const bool has_next = S.next(ui + 1, nxt);
;         const char* nA = cA; const char* nB = cB; if (has_next) PG8_PTRS(nxt, nA, nB);
.LBB0_54:
	s_cmp_lt_i32 s30, 0
	s_cbranch_scc0 .Lrev_skip_54
	s_sub_i32 s8, 0x7f, s8
